# v6 + G epilogue peephole: 181 dead zero-initialisations in front of full-row DPP rotates removed
# baseline (speedup 1.0000x reference)
.LBB0_785:
	v_ffbh_u32_e32 v176, v199
	v_min_u32_e32 v178, 32, v176
	v_lshlrev_b64 v[176:177], v178, v[198:199]
	v_min_u32_e32 v176, 1, v176
	v_or_b32_e32 v176, v177, v176
	v_cvt_f32_u32_e32 v176, v176
	v_sub_u32_e32 v178, 32, v178
	v_ffbh_u32_e32 v177, v197
	v_min_u32_e32 v179, 32, v177
	v_ldexp_f32 v176, v176, v178
	v_mul_f32_e32 v176, 0x35800000, v176
	v_fmamk_f32 v176, v176, 0x3a000000, v232
	v_mul_f32_e32 v178, 0x4b800000, v176
	v_cmp_gt_f32_e32 vcc, s5, v176
	s_nop 1
	v_cndmask_b32_e32 v176, v176, v178, vcc
	v_rsq_f32_e32 v178, v176
	v_lshlrev_b64 v[176:177], v179, v[196:197]
	v_min_u32_e32 v176, 1, v176
	v_or_b32_e32 v176, v177, v176
	v_cvt_f32_u32_e32 v176, v176
	v_mul_f32_e32 v196, 0x45800000, v178
	v_cndmask_b32_e32 v196, v178, v196, vcc
	v_pk_mul_f32 v[198:199], v[112:113], v[196:197] op_sel_hi:[1,0]
	v_sub_u32_e32 v112, 32, v179
	v_ldexp_f32 v112, v176, v112
	v_mul_f32_e32 v112, 0x35800000, v112
	v_fmamk_f32 v112, v112, 0x3a000000, v232
	v_mul_f32_e32 v113, 0x4b800000, v112
	v_cmp_gt_f32_e32 vcc, s5, v112
	v_pk_mul_f32 v[202:203], v[102:103], v[196:197] op_sel_hi:[1,0]
	v_pk_mul_f32 v[204:205], v[110:111], v[196:197] op_sel_hi:[1,0]
	v_cndmask_b32_e32 v112, v112, v113, vcc
	v_rsq_f32_e32 v112, v112
	v_pk_mul_f32 v[200:201], v[104:105], v[196:197] op_sel_hi:[1,0]
	v_mul_f32_e32 v102, 0x45800000, v112
	v_cndmask_b32_e32 v110, v112, v102, vcc
	v_pk_mul_f32 v[104:105], v[108:109], v[110:111] op_sel_hi:[1,0]
	s_waitcnt lgkmcnt(1)
	v_mov_b32_dpp v108, v168 row_ror:2 row_mask:0xf bank_mask:0xf
	v_mov_b32_dpp v109, v169 row_ror:2 row_mask:0xf bank_mask:0xf
	v_mov_b32_dpp v102, v168 row_ror:1 row_mask:0xf bank_mask:0xf
	v_mov_b32_dpp v108, v156 row_shr:2 row_mask:0xf bank_mask:0xf
	v_mov_b32_dpp v103, v169 row_ror:1 row_mask:0xf bank_mask:0xf
	v_mov_b32_dpp v109, v157 row_shr:2 row_mask:0xf bank_mask:0xf
	v_mov_b32_dpp v102, v156 row_shr:1 row_mask:0xf bank_mask:0xf
	v_mov_b32_dpp v103, v157 row_shr:1 row_mask:0xf bank_mask:0xf
	s_waitcnt vmcnt(4)
	v_pk_fma_f32 v[108:109], v[138:139], v[108:109], v[150:151]
	v_pk_fma_f32 v[102:103], v[142:143], v[102:103], v[108:109]
	v_pk_fma_f32 v[102:103], v[156:157], v[146:147], v[102:103]
	v_mul_f32_e32 v108, 0xbfb8aa3b, v102
	v_mul_f32_e32 v109, 0xbfb8aa3b, v103
	v_exp_f32_e32 v108, v108
	v_exp_f32_e32 v109, v109
	s_waitcnt lgkmcnt(0)
	v_mov_b32_dpp v168, v164 row_ror:2 row_mask:0xf bank_mask:0xf
	v_mov_b32_dpp v169, v165 row_ror:2 row_mask:0xf bank_mask:0xf
	v_add_f32_e32 v108, 1.0, v108
	v_add_f32_e32 v109, 1.0, v109
	v_rcp_f32_e32 v108, v108
	v_rcp_f32_e32 v109, v109
	v_mov_b32_dpp v112, v164 row_ror:1 row_mask:0xf bank_mask:0xf
	v_mov_b32_dpp v168, v160 row_shr:2 row_mask:0xf bank_mask:0xf
	v_mov_b32_dpp v113, v165 row_ror:1 row_mask:0xf bank_mask:0xf
	v_mov_b32_dpp v169, v161 row_shr:2 row_mask:0xf bank_mask:0xf
	v_mov_b32_dpp v112, v160 row_shr:1 row_mask:0xf bank_mask:0xf
	v_mov_b32_dpp v113, v161 row_shr:1 row_mask:0xf bank_mask:0xf
	s_waitcnt vmcnt(0)
	v_pk_fma_f32 v[164:165], v[114:115], v[168:169], v[130:131]
	v_pk_mul_f32 v[102:103], v[102:103], v[108:109]
	v_pk_fma_f32 v[112:113], v[122:123], v[112:113], v[164:165]
	v_pk_fma_f32 v[112:113], v[160:161], v[126:127], v[112:113]
	v_pk_mul_f32 v[102:103], v[112:113], v[102:103]
	v_mov_b32_dpp v108, v170 row_ror:1 row_mask:0xf bank_mask:0xf
	v_mov_b32_dpp v112, v170 row_ror:2 row_mask:0xf bank_mask:0xf
	v_mov_b32_dpp v113, v171 row_ror:2 row_mask:0xf bank_mask:0xf
	v_mov_b32_dpp v109, v171 row_ror:1 row_mask:0xf bank_mask:0xf
	v_mov_b32_dpp v112, v158 row_shr:2 row_mask:0xf bank_mask:0xf
	v_mov_b32_dpp v113, v159 row_shr:2 row_mask:0xf bank_mask:0xf
	v_mov_b32_dpp v108, v158 row_shr:1 row_mask:0xf bank_mask:0xf
	v_mov_b32_dpp v109, v159 row_shr:1 row_mask:0xf bank_mask:0xf
	v_pk_fma_f32 v[112:113], v[140:141], v[112:113], v[152:153]
	v_pk_mul_f32 v[106:107], v[106:107], v[110:111] op_sel_hi:[1,0]
	v_pk_fma_f32 v[108:109], v[144:145], v[108:109], v[112:113]
	v_pk_mul_f32 v[100:101], v[100:101], v[110:111] op_sel_hi:[1,0]
	v_pk_fma_f32 v[108:109], v[158:159], v[148:149], v[108:109]
	v_pk_mul_f32 v[98:99], v[98:99], v[110:111] op_sel_hi:[1,0]
	v_mul_f32_e32 v111, 0xbfb8aa3b, v108
	v_exp_f32_e32 v111, v111
	v_mul_f32_e32 v112, 0xbfb8aa3b, v109
	v_exp_f32_e32 v113, v112
	v_add_f32_e32 v111, 1.0, v111
	v_rcp_f32_e32 v112, v111
	v_add_f32_e32 v111, 1.0, v113
	v_mov_b32_dpp v168, v166 row_ror:2 row_mask:0xf bank_mask:0xf
	v_mov_b32_dpp v169, v167 row_ror:2 row_mask:0xf bank_mask:0xf
	v_rcp_f32_e32 v113, v111
	v_mov_b32_dpp v164, v166 row_ror:1 row_mask:0xf bank_mask:0xf
	v_mov_b32_dpp v168, v162 row_shr:2 row_mask:0xf bank_mask:0xf
	v_mov_b32_dpp v165, v167 row_ror:1 row_mask:0xf bank_mask:0xf
	v_mov_b32_dpp v169, v163 row_shr:2 row_mask:0xf bank_mask:0xf
	v_mov_b32_dpp v164, v162 row_shr:1 row_mask:0xf bank_mask:0xf
	v_mov_b32_dpp v165, v163 row_shr:1 row_mask:0xf bank_mask:0xf
	v_pk_fma_f32 v[166:167], v[116:117], v[168:169], v[132:133]
	v_pk_mul_f32 v[108:109], v[108:109], v[112:113]
	v_pk_fma_f32 v[164:165], v[124:125], v[164:165], v[166:167]
	v_cvt_pk_bf16_f32 v112, v102, v103
	v_pk_fma_f32 v[164:165], v[162:163], v[128:129], v[164:165]
	v_lshlrev_b64 v[102:103], 1, v[188:189]
	v_pk_mul_f32 v[108:109], v[164:165], v[108:109]
	v_mov_b64_e32 v[164:165], s[64:65]
	v_cvt_pk_bf16_f32 v113, v108, v109
	v_mad_i64_i32 v[108:109], s[6:7], v186, s29, v[164:165]
	v_lshl_add_u64 v[166:167], v[108:109], 0, v[102:103]
	global_store_dwordx2 v[166:167], v[112:113], off
	v_mov_b32_e32 v112, 0
	v_mov_b32_dpp v166, v156 row_ror:2 row_mask:0xf bank_mask:0xf
	v_mov_b32_dpp v167, v157 row_ror:2 row_mask:0xf bank_mask:0xf
	v_mov_b32_dpp v112, v156 row_ror:1 row_mask:0xf bank_mask:0xf
	v_mov_b32_dpp v166, v204 row_shr:2 row_mask:0xf bank_mask:0xf
	v_mov_b32_dpp v113, v157 row_ror:1 row_mask:0xf bank_mask:0xf
	v_mov_b32_dpp v167, v205 row_shr:2 row_mask:0xf bank_mask:0xf
	v_mov_b32_dpp v112, v204 row_shr:1 row_mask:0xf bank_mask:0xf
	v_mov_b32_dpp v156, v160 row_ror:1 row_mask:0xf bank_mask:0xf
	v_mov_b32_dpp v168, v160 row_ror:2 row_mask:0xf bank_mask:0xf
	v_mov_b32_dpp v113, v205 row_shr:1 row_mask:0xf bank_mask:0xf
	v_mov_b32_dpp v157, v161 row_ror:1 row_mask:0xf bank_mask:0xf
	v_mov_b32_dpp v169, v161 row_ror:2 row_mask:0xf bank_mask:0xf
	v_pk_fma_f32 v[160:161], v[138:139], v[166:167], v[150:151]
	v_mov_b32_dpp v168, v202 row_shr:2 row_mask:0xf bank_mask:0xf
	v_pk_fma_f32 v[112:113], v[142:143], v[112:113], v[160:161]
	v_mov_b32_dpp v169, v203 row_shr:2 row_mask:0xf bank_mask:0xf
	v_pk_fma_f32 v[112:113], v[204:205], v[146:147], v[112:113]
	v_mov_b32_dpp v156, v202 row_shr:1 row_mask:0xf bank_mask:0xf
	v_mul_f32_e32 v111, 0xbfb8aa3b, v112
	v_exp_f32_e32 v111, v111
	v_mul_f32_e32 v160, 0xbfb8aa3b, v113
	v_exp_f32_e32 v161, v160
	v_mov_b32_dpp v157, v203 row_shr:1 row_mask:0xf bank_mask:0xf
	v_add_f32_e32 v111, 1.0, v111
	v_rcp_f32_e32 v160, v111
	v_add_f32_e32 v111, 1.0, v161
	v_rcp_f32_e32 v161, v111
	v_pk_fma_f32 v[166:167], v[114:115], v[168:169], v[130:131]
	s_andn2_b64 vcc, exec, s[88:89]
	v_pk_fma_f32 v[156:157], v[122:123], v[156:157], v[166:167]
	v_pk_mul_f32 v[112:113], v[112:113], v[160:161]
	v_pk_fma_f32 v[156:157], v[202:203], v[126:127], v[156:157]
	v_pk_mul_f32 v[112:113], v[156:157], v[112:113]
	v_mov_b32_dpp v160, v158 row_ror:2 row_mask:0xf bank_mask:0xf
	v_mov_b32_dpp v161, v159 row_ror:2 row_mask:0xf bank_mask:0xf
	v_mov_b32_dpp v156, v158 row_ror:1 row_mask:0xf bank_mask:0xf
	v_mov_b32_dpp v160, v198 row_shr:2 row_mask:0xf bank_mask:0xf
	v_mov_b32_dpp v157, v159 row_ror:1 row_mask:0xf bank_mask:0xf
	v_mov_b32_dpp v161, v199 row_shr:2 row_mask:0xf bank_mask:0xf
	v_mov_b32_dpp v156, v198 row_shr:1 row_mask:0xf bank_mask:0xf
	v_mov_b32_dpp v157, v199 row_shr:1 row_mask:0xf bank_mask:0xf
	v_pk_fma_f32 v[160:161], v[140:141], v[160:161], v[152:153]
	v_pk_fma_f32 v[156:157], v[144:145], v[156:157], v[160:161]
	v_pk_fma_f32 v[156:157], v[198:199], v[148:149], v[156:157]
	v_mul_f32_e32 v111, 0xbfb8aa3b, v156
	v_exp_f32_e32 v111, v111
	v_mul_f32_e32 v160, 0xbfb8aa3b, v157
	v_exp_f32_e32 v161, v160
	v_mov_b32_dpp v166, v162 row_ror:2 row_mask:0xf bank_mask:0xf
	v_add_f32_e32 v111, 1.0, v111
	v_rcp_f32_e32 v160, v111
	v_add_f32_e32 v111, 1.0, v161
	v_mov_b32_dpp v167, v163 row_ror:2 row_mask:0xf bank_mask:0xf
	v_rcp_f32_e32 v161, v111
	v_mov_b32_dpp v158, v162 row_ror:1 row_mask:0xf bank_mask:0xf
	v_mov_b32_dpp v166, v200 row_shr:2 row_mask:0xf bank_mask:0xf
	v_mov_b32_dpp v159, v163 row_ror:1 row_mask:0xf bank_mask:0xf
	v_mov_b32_dpp v167, v201 row_shr:2 row_mask:0xf bank_mask:0xf
	v_mov_b32_dpp v158, v200 row_shr:1 row_mask:0xf bank_mask:0xf
	v_mov_b32_dpp v159, v201 row_shr:1 row_mask:0xf bank_mask:0xf
	v_pk_fma_f32 v[162:163], v[116:117], v[166:167], v[132:133]
	v_pk_mul_f32 v[156:157], v[156:157], v[160:161]
	v_pk_fma_f32 v[158:159], v[124:125], v[158:159], v[162:163]
	v_add_u32_e32 v111, 16, v186
	v_pk_fma_f32 v[158:159], v[200:201], v[128:129], v[158:159]
	v_pk_mul_f32 v[156:157], v[158:159], v[156:157]
	v_cvt_pk_bf16_f32 v158, v112, v113
	v_mad_i64_i32 v[112:113], s[6:7], v111, s29, v[164:165]
	v_cvt_pk_bf16_f32 v159, v156, v157
	v_lshl_add_u64 v[156:157], v[112:113], 0, v[102:103]
	global_store_dwordx2 v[156:157], v[158:159], off
	v_mov_b32_dpp v158, v204 row_ror:2 row_mask:0xf bank_mask:0xf
	v_mov_b32_dpp v159, v205 row_ror:2 row_mask:0xf bank_mask:0xf
	v_mov_b32_dpp v156, v204 row_ror:1 row_mask:0xf bank_mask:0xf
	v_mov_b32_dpp v158, v106 row_shr:2 row_mask:0xf bank_mask:0xf
	v_mov_b32_dpp v157, v205 row_ror:1 row_mask:0xf bank_mask:0xf
	v_mov_b32_dpp v159, v107 row_shr:2 row_mask:0xf bank_mask:0xf
	v_mov_b32_dpp v156, v106 row_shr:1 row_mask:0xf bank_mask:0xf
	v_mov_b32_dpp v157, v107 row_shr:1 row_mask:0xf bank_mask:0xf
	v_pk_fma_f32 v[158:159], v[138:139], v[158:159], v[150:151]
	v_pk_fma_f32 v[156:157], v[142:143], v[156:157], v[158:159]
	v_pk_fma_f32 v[156:157], v[106:107], v[146:147], v[156:157]
	v_mov_b32_dpp v162, v202 row_ror:2 row_mask:0xf bank_mask:0xf
	v_mul_f32_e32 v111, 0xbfb8aa3b, v156
	v_exp_f32_e32 v111, v111
	v_mul_f32_e32 v158, 0xbfb8aa3b, v157
	v_exp_f32_e32 v159, v158
	v_add_f32_e32 v111, 1.0, v111
	v_rcp_f32_e32 v158, v111
	v_add_f32_e32 v111, 1.0, v159
	v_mov_b32_dpp v163, v203 row_ror:2 row_mask:0xf bank_mask:0xf
	v_rcp_f32_e32 v159, v111
	v_mov_b32_dpp v160, v202 row_ror:1 row_mask:0xf bank_mask:0xf
	v_mov_b32_dpp v162, v98 row_shr:2 row_mask:0xf bank_mask:0xf
	v_mov_b32_dpp v161, v203 row_ror:1 row_mask:0xf bank_mask:0xf
	v_mov_b32_dpp v163, v99 row_shr:2 row_mask:0xf bank_mask:0xf
	v_mov_b32_dpp v160, v98 row_shr:1 row_mask:0xf bank_mask:0xf
	v_mov_b32_dpp v161, v99 row_shr:1 row_mask:0xf bank_mask:0xf
	v_pk_fma_f32 v[162:163], v[114:115], v[162:163], v[130:131]
	v_pk_mul_f32 v[156:157], v[156:157], v[158:159]
	v_pk_fma_f32 v[160:161], v[122:123], v[160:161], v[162:163]
	v_pk_fma_f32 v[160:161], v[98:99], v[126:127], v[160:161]
	v_pk_mul_f32 v[156:157], v[160:161], v[156:157]
	v_mov_b32_dpp v158, v198 row_ror:1 row_mask:0xf bank_mask:0xf
	v_mov_b32_dpp v160, v198 row_ror:2 row_mask:0xf bank_mask:0xf
	v_mov_b32_dpp v161, v199 row_ror:2 row_mask:0xf bank_mask:0xf
	v_mov_b32_dpp v159, v199 row_ror:1 row_mask:0xf bank_mask:0xf
	v_mov_b32_dpp v160, v104 row_shr:2 row_mask:0xf bank_mask:0xf
	v_mov_b32_dpp v161, v105 row_shr:2 row_mask:0xf bank_mask:0xf
	v_mov_b32_dpp v158, v104 row_shr:1 row_mask:0xf bank_mask:0xf
	v_mov_b32_dpp v159, v105 row_shr:1 row_mask:0xf bank_mask:0xf
	v_pk_fma_f32 v[160:161], v[140:141], v[160:161], v[152:153]
	v_pk_fma_f32 v[158:159], v[144:145], v[158:159], v[160:161]
	v_pk_fma_f32 v[158:159], v[104:105], v[148:149], v[158:159]
	v_mul_f32_e32 v111, 0xbfb8aa3b, v158
	v_exp_f32_e32 v111, v111
	v_mul_f32_e32 v160, 0xbfb8aa3b, v159
	v_exp_f32_e32 v161, v160
	v_mov_b32_dpp v166, v200 row_ror:2 row_mask:0xf bank_mask:0xf
	v_add_f32_e32 v111, 1.0, v111
	v_rcp_f32_e32 v160, v111
	v_add_f32_e32 v111, 1.0, v161
	v_mov_b32_dpp v167, v201 row_ror:2 row_mask:0xf bank_mask:0xf
	v_rcp_f32_e32 v161, v111
	v_mov_b32_dpp v162, v200 row_ror:1 row_mask:0xf bank_mask:0xf
	v_mov_b32_dpp v166, v100 row_shr:2 row_mask:0xf bank_mask:0xf
	v_mov_b32_dpp v163, v201 row_ror:1 row_mask:0xf bank_mask:0xf
	v_mov_b32_dpp v167, v101 row_shr:2 row_mask:0xf bank_mask:0xf
	v_mov_b32_dpp v162, v100 row_shr:1 row_mask:0xf bank_mask:0xf
	v_mov_b32_dpp v163, v101 row_shr:1 row_mask:0xf bank_mask:0xf
	v_pk_fma_f32 v[166:167], v[116:117], v[166:167], v[132:133]
	v_pk_mul_f32 v[158:159], v[158:159], v[160:161]
	v_pk_fma_f32 v[162:163], v[124:125], v[162:163], v[166:167]
	v_add_u32_e32 v111, 32, v186
	v_pk_fma_f32 v[162:163], v[100:101], v[128:129], v[162:163]
	v_cvt_pk_bf16_f32 v156, v156, v157
	v_pk_mul_f32 v[158:159], v[162:163], v[158:159]
	v_cvt_pk_bf16_f32 v157, v158, v159
	v_mad_i64_i32 v[158:159], s[6:7], v111, s29, v[164:165]
	v_lshl_add_u64 v[160:161], v[158:159], 0, v[102:103]
	global_store_dwordx2 v[160:161], v[156:157], off
	v_mov_b32_e32 v156, 0
	v_mov_b32_dpp v160, v106 row_ror:2 row_mask:0xf bank_mask:0xf
	v_mov_b32_dpp v161, v107 row_ror:2 row_mask:0xf bank_mask:0xf
	v_mov_b32_dpp v156, v106 row_ror:1 row_mask:0xf bank_mask:0xf
	v_mov_b32_dpp v160, v134 row_shr:2 row_mask:0xf bank_mask:0xf
	v_mov_b32_dpp v157, v107 row_ror:1 row_mask:0xf bank_mask:0xf
	v_mov_b32_dpp v161, v135 row_shr:2 row_mask:0xf bank_mask:0xf
	v_mov_b32_dpp v156, v134 row_shr:1 row_mask:0xf bank_mask:0xf
	v_mov_b32_dpp v106, v98 row_ror:1 row_mask:0xf bank_mask:0xf
	v_mov_b32_dpp v162, v98 row_ror:2 row_mask:0xf bank_mask:0xf
	v_mov_b32_dpp v157, v135 row_shr:1 row_mask:0xf bank_mask:0xf
	v_mov_b32_dpp v107, v99 row_ror:1 row_mask:0xf bank_mask:0xf
	v_mov_b32_dpp v163, v99 row_ror:2 row_mask:0xf bank_mask:0xf
	v_pk_fma_f32 v[98:99], v[138:139], v[160:161], v[150:151]
	v_mov_b32_dpp v162, v118 row_shr:2 row_mask:0xf bank_mask:0xf
	v_pk_fma_f32 v[98:99], v[142:143], v[156:157], v[98:99]
	v_mov_b32_dpp v163, v119 row_shr:2 row_mask:0xf bank_mask:0xf
	v_pk_fma_f32 v[98:99], v[134:135], v[146:147], v[98:99]
	v_mov_b32_dpp v106, v118 row_shr:1 row_mask:0xf bank_mask:0xf
	v_mul_f32_e32 v111, 0xbfb8aa3b, v98
	v_exp_f32_e32 v111, v111
	v_mul_f32_e32 v134, 0xbfb8aa3b, v99
	v_exp_f32_e32 v135, v134
	v_mov_b32_dpp v107, v119 row_shr:1 row_mask:0xf bank_mask:0xf
	v_add_f32_e32 v111, 1.0, v111
	v_rcp_f32_e32 v134, v111
	v_add_f32_e32 v111, 1.0, v135
	v_rcp_f32_e32 v135, v111
	v_pk_fma_f32 v[156:157], v[114:115], v[162:163], v[130:131]
	v_pk_mul_f32 v[98:99], v[98:99], v[134:135]
	v_pk_fma_f32 v[106:107], v[122:123], v[106:107], v[156:157]
	v_pk_fma_f32 v[106:107], v[118:119], v[126:127], v[106:107]
	v_pk_mul_f32 v[98:99], v[106:107], v[98:99]
	v_mov_b32_dpp v118, v104 row_ror:2 row_mask:0xf bank_mask:0xf
	v_mov_b32_dpp v119, v105 row_ror:2 row_mask:0xf bank_mask:0xf
	v_mov_b32_dpp v106, v104 row_ror:1 row_mask:0xf bank_mask:0xf
	v_mov_b32_dpp v118, v136 row_shr:2 row_mask:0xf bank_mask:0xf
	v_mov_b32_dpp v107, v105 row_ror:1 row_mask:0xf bank_mask:0xf
	v_mov_b32_dpp v119, v137 row_shr:2 row_mask:0xf bank_mask:0xf
	v_mov_b32_dpp v106, v136 row_shr:1 row_mask:0xf bank_mask:0xf
	v_mov_b32_dpp v104, v100 row_ror:1 row_mask:0xf bank_mask:0xf
	v_mov_b32_dpp v134, v100 row_ror:2 row_mask:0xf bank_mask:0xf
	v_mov_b32_dpp v107, v137 row_shr:1 row_mask:0xf bank_mask:0xf
	v_mov_b32_dpp v105, v101 row_ror:1 row_mask:0xf bank_mask:0xf
	v_mov_b32_dpp v135, v101 row_ror:2 row_mask:0xf bank_mask:0xf
	v_pk_fma_f32 v[100:101], v[140:141], v[118:119], v[152:153]
	v_mov_b32_dpp v134, v120 row_shr:2 row_mask:0xf bank_mask:0xf
	v_pk_fma_f32 v[100:101], v[144:145], v[106:107], v[100:101]
	v_mov_b32_dpp v135, v121 row_shr:2 row_mask:0xf bank_mask:0xf
	v_pk_fma_f32 v[100:101], v[136:137], v[148:149], v[100:101]
	v_mov_b32_dpp v104, v120 row_shr:1 row_mask:0xf bank_mask:0xf
	v_mul_f32_e32 v106, 0xbfb8aa3b, v100
	v_mul_f32_e32 v107, 0xbfb8aa3b, v101
	v_exp_f32_e32 v106, v106
	v_exp_f32_e32 v107, v107
	v_mov_b32_dpp v105, v121 row_shr:1 row_mask:0xf bank_mask:0xf
	v_pk_fma_f32 v[118:119], v[116:117], v[134:135], v[132:133]
	v_add_f32_e32 v106, 1.0, v106
	v_add_f32_e32 v107, 1.0, v107
	v_rcp_f32_e32 v106, v106
	v_rcp_f32_e32 v107, v107
	v_pk_fma_f32 v[104:105], v[124:125], v[104:105], v[118:119]
	v_cvt_pk_bf16_f32 v98, v98, v99
	v_pk_fma_f32 v[104:105], v[120:121], v[128:129], v[104:105]
	v_pk_mul_f32 v[100:101], v[100:101], v[106:107]
	v_add_u32_e32 v121, s83, v155
	v_pk_mul_f32 v[100:101], v[104:105], v[100:101]
	v_mov_b32_e32 v155, 0
	v_cvt_pk_bf16_f32 v99, v100, v101
	v_add_u32_e32 v100, 48, v186
	v_mad_i64_i32 v[118:119], s[6:7], v100, s29, v[164:165]
	v_lshl_add_u64 v[100:101], v[118:119], 0, v[102:103]
	global_store_dwordx2 v[100:101], v[98:99], off
	v_cndmask_b32_e64 v98, 0, 1, s[88:89]
	v_cmp_ne_u32_e64 s[16:17], 1, v98
	v_mov_b32_e32 v156, 0
	v_mov_b32_e32 v157, 0
	v_mov_b32_e32 v98, 0
	v_mov_b32_e32 v99, 0
	v_mov_b32_e32 v100, 0
	v_mov_b32_e32 v101, 0
	s_cbranch_vccnz .LBB0_787
	v_lshl_add_u32 v98, v121, 6, 0
	v_add_u32_e32 v104, 0x20000, v98
	ds_read_b128 v[98:101], v104
	ds_read_b128 v[154:157], v104 offset:32
.LBB0_787:
	v_ffbh_u32_e32 v104, v195
	v_min_u32_e32 v106, 32, v104
	v_lshlrev_b64 v[104:105], v106, v[194:195]
	v_min_u32_e32 v104, 1, v104
	v_or_b32_e32 v104, v105, v104
	v_cvt_f32_u32_e32 v104, v104
	v_sub_u32_e32 v106, 32, v106
	v_ffbh_u32_e32 v105, v193
	v_min_u32_e32 v107, 32, v105
	v_ldexp_f32 v104, v104, v106
	v_mul_f32_e32 v104, 0x35800000, v104
	v_fmamk_f32 v104, v104, 0x3a000000, v232
	v_mul_f32_e32 v106, 0x4b800000, v104
	v_cmp_gt_f32_e32 vcc, s5, v104
	v_mov_b32_e32 v160, 0
	v_mov_b32_e32 v161, 0
	v_cndmask_b32_e32 v104, v104, v106, vcc
	v_rsq_f32_e32 v106, v104
	v_lshlrev_b64 v[104:105], v107, v[192:193]
	v_min_u32_e32 v104, 1, v104
	v_or_b32_e32 v104, v105, v104
	v_cvt_f32_u32_e32 v104, v104
	v_sub_u32_e32 v105, 32, v107
	v_mul_f32_e32 v111, 0x45800000, v106
	v_cndmask_b32_e32 v120, v106, v111, vcc
	v_ldexp_f32 v104, v104, v105
	v_mul_f32_e32 v104, 0x35800000, v104
	v_fmamk_f32 v104, v104, 0x3a000000, v232
	v_mul_f32_e32 v105, 0x4b800000, v104
	v_cmp_gt_f32_e32 vcc, s5, v104
	v_pk_mul_f32 v[106:107], v[74:75], v[120:121] op_sel_hi:[1,0]
	v_ffbh_u32_e32 v74, v191
	v_cndmask_b32_e32 v104, v104, v105, vcc
	v_rsq_f32_e32 v111, v104
	v_pk_mul_f32 v[104:105], v[78:79], v[120:121] op_sel_hi:[1,0]
	v_pk_mul_f32 v[78:79], v[76:77], v[120:121] op_sel_hi:[1,0]
	v_min_u32_e32 v77, 32, v74
	v_lshlrev_b64 v[74:75], v77, v[190:191]
	v_min_u32_e32 v74, 1, v74
	v_or_b32_e32 v74, v75, v74
	v_cvt_f32_u32_e32 v74, v74
	v_sub_u32_e32 v75, 32, v77
	v_mul_f32_e32 v76, 0x45800000, v111
	v_cndmask_b32_e32 v134, v111, v76, vcc
	v_ldexp_f32 v74, v74, v75
	v_mul_f32_e32 v74, 0x35800000, v74
	v_fmamk_f32 v74, v74, 0x3a000000, v232
	v_mul_f32_e32 v75, 0x4b800000, v74
	v_cmp_gt_f32_e32 vcc, s5, v74
	v_pk_mul_f32 v[76:77], v[70:71], v[134:135] op_sel_hi:[1,0]
	v_pk_mul_f32 v[70:71], v[64:65], v[134:135] op_sel_hi:[1,0]
	v_cndmask_b32_e32 v74, v74, v75, vcc
	v_rsq_f32_e32 v111, v74
	v_pk_mul_f32 v[74:75], v[62:63], v[134:135] op_sel_hi:[1,0]
	s_waitcnt lgkmcnt(0)
	v_mov_b32_dpp v160, v154 row_ror:2 row_mask:0xf bank_mask:0xf
	v_mov_b32_dpp v161, v155 row_ror:2 row_mask:0xf bank_mask:0xf
	v_mul_f32_e32 v62, 0x45800000, v111
	v_cndmask_b32_e32 v136, v111, v62, vcc
	v_pk_mul_f32 v[62:63], v[68:69], v[136:137] op_sel_hi:[1,0]
	v_pk_mul_f32 v[64:65], v[66:67], v[136:137] op_sel_hi:[1,0]
	v_mov_b32_dpp v68, v98 row_ror:2 row_mask:0xf bank_mask:0xf
	v_mov_b32_dpp v69, v99 row_ror:2 row_mask:0xf bank_mask:0xf
	v_mov_b32_dpp v66, v98 row_ror:1 row_mask:0xf bank_mask:0xf
	v_mov_b32_dpp v68, v104 row_shr:2 row_mask:0xf bank_mask:0xf
	v_mov_b32_dpp v67, v99 row_ror:1 row_mask:0xf bank_mask:0xf
	v_mov_b32_dpp v69, v105 row_shr:2 row_mask:0xf bank_mask:0xf
	v_mov_b32_dpp v66, v104 row_shr:1 row_mask:0xf bank_mask:0xf
	v_mov_b32_dpp v67, v105 row_shr:1 row_mask:0xf bank_mask:0xf
	v_pk_fma_f32 v[68:69], v[138:139], v[68:69], v[150:151]
	v_pk_fma_f32 v[66:67], v[142:143], v[66:67], v[68:69]
	v_pk_fma_f32 v[66:67], v[104:105], v[146:147], v[66:67]
	v_mov_b32_dpp v98, v154 row_ror:1 row_mask:0xf bank_mask:0xf
	v_mul_f32_e32 v68, 0xbfb8aa3b, v66
	v_mul_f32_e32 v69, 0xbfb8aa3b, v67
	v_exp_f32_e32 v68, v68
	v_exp_f32_e32 v69, v69
	v_mov_b32_dpp v160, v106 row_shr:2 row_mask:0xf bank_mask:0xf
	v_mov_b32_dpp v99, v155 row_ror:1 row_mask:0xf bank_mask:0xf
	v_add_f32_e32 v68, 1.0, v68
	v_add_f32_e32 v69, 1.0, v69
	v_rcp_f32_e32 v68, v68
	v_rcp_f32_e32 v69, v69
	v_mov_b32_dpp v161, v107 row_shr:2 row_mask:0xf bank_mask:0xf
	v_mov_b32_dpp v98, v106 row_shr:1 row_mask:0xf bank_mask:0xf
	v_mov_b32_dpp v99, v107 row_shr:1 row_mask:0xf bank_mask:0xf
	v_pk_fma_f32 v[154:155], v[114:115], v[160:161], v[130:131]
	v_pk_mul_f32 v[66:67], v[66:67], v[68:69]
	v_pk_fma_f32 v[98:99], v[122:123], v[98:99], v[154:155]
	v_pk_mul_f32 v[80:81], v[80:81], v[120:121] op_sel_hi:[1,0]
	v_pk_fma_f32 v[98:99], v[106:107], v[126:127], v[98:99]
	v_pk_mul_f32 v[66:67], v[98:99], v[66:67]
	v_mov_b32_e32 v69, 0
	v_mov_b32_dpp v98, v100 row_ror:2 row_mask:0xf bank_mask:0xf
	v_mov_b32_dpp v99, v101 row_ror:2 row_mask:0xf bank_mask:0xf
	v_mov_b32_dpp v68, v100 row_ror:1 row_mask:0xf bank_mask:0xf
	v_mov_b32_dpp v98, v80 row_shr:2 row_mask:0xf bank_mask:0xf
	v_mov_b32_dpp v69, v101 row_ror:1 row_mask:0xf bank_mask:0xf
	v_mov_b32_dpp v99, v81 row_shr:2 row_mask:0xf bank_mask:0xf
	v_mov_b32_dpp v68, v80 row_shr:1 row_mask:0xf bank_mask:0xf
	v_mov_b32_dpp v69, v81 row_shr:1 row_mask:0xf bank_mask:0xf
	v_pk_fma_f32 v[98:99], v[140:141], v[98:99], v[152:153]
	v_pk_fma_f32 v[68:69], v[144:145], v[68:69], v[98:99]
	v_pk_fma_f32 v[68:69], v[80:81], v[148:149], v[68:69]
	v_mul_f32_e32 v98, 0xbfb8aa3b, v68
	v_mul_f32_e32 v99, 0xbfb8aa3b, v69
	v_exp_f32_e32 v98, v98
	v_exp_f32_e32 v99, v99
	v_mov_b32_dpp v154, v156 row_ror:2 row_mask:0xf bank_mask:0xf
	v_add_f32_e32 v98, 1.0, v98
	v_add_f32_e32 v99, 1.0, v99
	v_mov_b32_dpp v155, v157 row_ror:2 row_mask:0xf bank_mask:0xf
	v_rcp_f32_e32 v98, v98
	v_rcp_f32_e32 v99, v99
	v_mov_b32_dpp v100, v156 row_ror:1 row_mask:0xf bank_mask:0xf
	v_mov_b32_dpp v154, v78 row_shr:2 row_mask:0xf bank_mask:0xf
	v_mov_b32_dpp v101, v157 row_ror:1 row_mask:0xf bank_mask:0xf
	v_mov_b32_dpp v155, v79 row_shr:2 row_mask:0xf bank_mask:0xf
	v_mov_b32_dpp v100, v78 row_shr:1 row_mask:0xf bank_mask:0xf
	v_mov_b32_dpp v101, v79 row_shr:1 row_mask:0xf bank_mask:0xf
	v_pk_fma_f32 v[154:155], v[116:117], v[154:155], v[132:133]
	v_add_u32_e32 v111, 0x80, v186
	v_pk_fma_f32 v[100:101], v[124:125], v[100:101], v[154:155]
	v_pk_mul_f32 v[68:69], v[68:69], v[98:99]
	v_pk_fma_f32 v[100:101], v[78:79], v[128:129], v[100:101]
	v_cvt_pk_bf16_f32 v98, v66, v67
	v_mov_b64_e32 v[66:67], s[64:65]
	v_pk_mul_f32 v[68:69], v[100:101], v[68:69]
	v_mad_i64_i32 v[154:155], s[6:7], v111, s29, v[66:67]
	v_cvt_pk_bf16_f32 v99, v68, v69
	v_lshl_add_u64 v[68:69], v[154:155], 0, v[102:103]
	global_store_dwordx2 v[68:69], v[98:99], off
	v_mov_b32_dpp v98, v104 row_ror:2 row_mask:0xf bank_mask:0xf
	v_mov_b32_dpp v99, v105 row_ror:2 row_mask:0xf bank_mask:0xf
	v_mov_b32_dpp v68, v104 row_ror:1 row_mask:0xf bank_mask:0xf
	v_mov_b32_dpp v98, v76 row_shr:2 row_mask:0xf bank_mask:0xf
	v_mov_b32_dpp v69, v105 row_ror:1 row_mask:0xf bank_mask:0xf
	v_mov_b32_dpp v99, v77 row_shr:2 row_mask:0xf bank_mask:0xf
	v_mov_b32_dpp v68, v76 row_shr:1 row_mask:0xf bank_mask:0xf
	v_mov_b32_dpp v69, v77 row_shr:1 row_mask:0xf bank_mask:0xf
	v_pk_fma_f32 v[98:99], v[138:139], v[98:99], v[150:151]
	v_pk_fma_f32 v[68:69], v[142:143], v[68:69], v[98:99]
	v_pk_fma_f32 v[68:69], v[76:77], v[146:147], v[68:69]
	v_mul_f32_e32 v98, 0xbfb8aa3b, v68
	v_mul_f32_e32 v99, 0xbfb8aa3b, v69
	v_exp_f32_e32 v98, v98
	v_exp_f32_e32 v99, v99
	v_mov_b32_dpp v104, v106 row_ror:2 row_mask:0xf bank_mask:0xf
	v_add_f32_e32 v98, 1.0, v98
	v_add_f32_e32 v99, 1.0, v99
	v_mov_b32_dpp v105, v107 row_ror:2 row_mask:0xf bank_mask:0xf
	v_rcp_f32_e32 v98, v98
	v_rcp_f32_e32 v99, v99
	v_mov_b32_dpp v100, v106 row_ror:1 row_mask:0xf bank_mask:0xf
	v_mov_b32_dpp v104, v74 row_shr:2 row_mask:0xf bank_mask:0xf
	v_mov_b32_dpp v101, v107 row_ror:1 row_mask:0xf bank_mask:0xf
	v_mov_b32_dpp v105, v75 row_shr:2 row_mask:0xf bank_mask:0xf
	v_mov_b32_dpp v100, v74 row_shr:1 row_mask:0xf bank_mask:0xf
	v_mov_b32_dpp v101, v75 row_shr:1 row_mask:0xf bank_mask:0xf
	v_pk_fma_f32 v[104:105], v[114:115], v[104:105], v[130:131]
	v_pk_mul_f32 v[68:69], v[68:69], v[98:99]
	v_pk_fma_f32 v[100:101], v[122:123], v[100:101], v[104:105]
	v_pk_mul_f32 v[72:73], v[72:73], v[134:135] op_sel_hi:[1,0]
	v_pk_fma_f32 v[100:101], v[74:75], v[126:127], v[100:101]
	v_pk_mul_f32 v[68:69], v[100:101], v[68:69]
	v_mov_b32_e32 v99, 0
	v_mov_b32_dpp v100, v80 row_ror:2 row_mask:0xf bank_mask:0xf
	v_mov_b32_dpp v101, v81 row_ror:2 row_mask:0xf bank_mask:0xf
	v_mov_b32_dpp v98, v80 row_ror:1 row_mask:0xf bank_mask:0xf
	v_mov_b32_dpp v100, v72 row_shr:2 row_mask:0xf bank_mask:0xf
	v_mov_b32_dpp v99, v81 row_ror:1 row_mask:0xf bank_mask:0xf
	v_mov_b32_dpp v101, v73 row_shr:2 row_mask:0xf bank_mask:0xf
	v_mov_b32_dpp v98, v72 row_shr:1 row_mask:0xf bank_mask:0xf
	v_mov_b32_dpp v80, v78 row_ror:1 row_mask:0xf bank_mask:0xf
	v_mov_b32_dpp v104, v78 row_ror:2 row_mask:0xf bank_mask:0xf
	v_mov_b32_dpp v99, v73 row_shr:1 row_mask:0xf bank_mask:0xf
	v_mov_b32_dpp v81, v79 row_ror:1 row_mask:0xf bank_mask:0xf
	v_mov_b32_dpp v105, v79 row_ror:2 row_mask:0xf bank_mask:0xf
	v_pk_fma_f32 v[78:79], v[140:141], v[100:101], v[152:153]
	v_mov_b32_dpp v104, v70 row_shr:2 row_mask:0xf bank_mask:0xf
	v_pk_fma_f32 v[78:79], v[144:145], v[98:99], v[78:79]
	v_mov_b32_dpp v105, v71 row_shr:2 row_mask:0xf bank_mask:0xf
	v_pk_fma_f32 v[78:79], v[72:73], v[148:149], v[78:79]
	v_mov_b32_dpp v80, v70 row_shr:1 row_mask:0xf bank_mask:0xf
	v_mul_f32_e32 v98, 0xbfb8aa3b, v78
	v_mul_f32_e32 v99, 0xbfb8aa3b, v79
	v_exp_f32_e32 v98, v98
	v_exp_f32_e32 v99, v99
	v_mov_b32_dpp v81, v71 row_shr:1 row_mask:0xf bank_mask:0xf
	v_pk_fma_f32 v[100:101], v[116:117], v[104:105], v[132:133]
	v_add_f32_e32 v98, 1.0, v98
	v_add_f32_e32 v99, 1.0, v99
	v_rcp_f32_e32 v98, v98
	v_rcp_f32_e32 v99, v99
	v_pk_fma_f32 v[80:81], v[124:125], v[80:81], v[100:101]
	v_cvt_pk_bf16_f32 v68, v68, v69
	v_pk_fma_f32 v[80:81], v[70:71], v[128:129], v[80:81]
	v_pk_mul_f32 v[78:79], v[78:79], v[98:99]
	v_pk_mul_f32 v[58:59], v[58:59], v[136:137] op_sel_hi:[1,0]
	v_pk_mul_f32 v[78:79], v[80:81], v[78:79]
	v_cvt_pk_bf16_f32 v69, v78, v79
	v_add_u32_e32 v78, 0x90, v186
	v_mad_i64_i32 v[156:157], s[6:7], v78, s29, v[66:67]
	v_lshl_add_u64 v[78:79], v[156:157], 0, v[102:103]
	global_store_dwordx2 v[78:79], v[68:69], off
	v_mov_b32_e32 v68, 0
	v_mov_b32_dpp v78, v76 row_ror:2 row_mask:0xf bank_mask:0xf
	v_mov_b32_dpp v79, v77 row_ror:2 row_mask:0xf bank_mask:0xf
	v_mov_b32_dpp v68, v76 row_ror:1 row_mask:0xf bank_mask:0xf
	v_mov_b32_dpp v78, v64 row_shr:2 row_mask:0xf bank_mask:0xf
	v_mov_b32_dpp v69, v77 row_ror:1 row_mask:0xf bank_mask:0xf
	v_mov_b32_dpp v79, v65 row_shr:2 row_mask:0xf bank_mask:0xf
	v_mov_b32_dpp v68, v64 row_shr:1 row_mask:0xf bank_mask:0xf
	v_mov_b32_dpp v76, v74 row_ror:1 row_mask:0xf bank_mask:0xf
	v_mov_b32_dpp v80, v74 row_ror:2 row_mask:0xf bank_mask:0xf
	v_mov_b32_dpp v69, v65 row_shr:1 row_mask:0xf bank_mask:0xf
	v_mov_b32_dpp v77, v75 row_ror:1 row_mask:0xf bank_mask:0xf
	v_mov_b32_dpp v81, v75 row_ror:2 row_mask:0xf bank_mask:0xf
	v_pk_fma_f32 v[74:75], v[138:139], v[78:79], v[150:151]
	v_mov_b32_dpp v80, v58 row_shr:2 row_mask:0xf bank_mask:0xf
	v_pk_fma_f32 v[68:69], v[142:143], v[68:69], v[74:75]
	v_mov_b32_dpp v81, v59 row_shr:2 row_mask:0xf bank_mask:0xf
	v_pk_fma_f32 v[68:69], v[64:65], v[146:147], v[68:69]
	v_mov_b32_dpp v76, v58 row_shr:1 row_mask:0xf bank_mask:0xf
	v_mul_f32_e32 v74, 0xbfb8aa3b, v68
	v_mul_f32_e32 v75, 0xbfb8aa3b, v69
	v_exp_f32_e32 v74, v74
	v_exp_f32_e32 v75, v75
	v_mov_b32_dpp v77, v59 row_shr:1 row_mask:0xf bank_mask:0xf
	v_pk_fma_f32 v[78:79], v[114:115], v[80:81], v[130:131]
	v_add_f32_e32 v74, 1.0, v74
	v_add_f32_e32 v75, 1.0, v75
	v_rcp_f32_e32 v74, v74
	v_rcp_f32_e32 v75, v75
	v_pk_fma_f32 v[76:77], v[122:123], v[76:77], v[78:79]
	v_pk_fma_f32 v[76:77], v[58:59], v[126:127], v[76:77]
	v_pk_mul_f32 v[68:69], v[68:69], v[74:75]
	v_pk_mul_f32 v[68:69], v[76:77], v[68:69]
	v_mov_b32_dpp v76, v72 row_ror:2 row_mask:0xf bank_mask:0xf
	v_mov_b32_dpp v77, v73 row_ror:2 row_mask:0xf bank_mask:0xf
	v_mov_b32_dpp v74, v72 row_ror:1 row_mask:0xf bank_mask:0xf
	v_mov_b32_dpp v76, v62 row_shr:2 row_mask:0xf bank_mask:0xf
	v_mov_b32_dpp v75, v73 row_ror:1 row_mask:0xf bank_mask:0xf
	v_mov_b32_dpp v77, v63 row_shr:2 row_mask:0xf bank_mask:0xf
	v_mov_b32_dpp v74, v62 row_shr:1 row_mask:0xf bank_mask:0xf
	v_mov_b32_dpp v72, v70 row_ror:1 row_mask:0xf bank_mask:0xf
	v_mov_b32_dpp v78, v70 row_ror:2 row_mask:0xf bank_mask:0xf
	v_mov_b32_dpp v75, v63 row_shr:1 row_mask:0xf bank_mask:0xf
	v_mov_b32_dpp v73, v71 row_ror:1 row_mask:0xf bank_mask:0xf
	v_mov_b32_dpp v79, v71 row_ror:2 row_mask:0xf bank_mask:0xf
	v_pk_fma_f32 v[70:71], v[140:141], v[76:77], v[152:153]
	v_pk_mul_f32 v[60:61], v[60:61], v[136:137] op_sel_hi:[1,0]
	v_pk_fma_f32 v[70:71], v[144:145], v[74:75], v[70:71]
	v_cvt_pk_bf16_f32 v68, v68, v69
	v_pk_fma_f32 v[70:71], v[62:63], v[148:149], v[70:71]
	v_mov_b32_dpp v78, v60 row_shr:2 row_mask:0xf bank_mask:0xf
	v_mul_f32_e32 v74, 0xbfb8aa3b, v70
	v_mul_f32_e32 v75, 0xbfb8aa3b, v71
	v_exp_f32_e32 v74, v74
	v_exp_f32_e32 v75, v75
	v_mov_b32_dpp v79, v61 row_shr:2 row_mask:0xf bank_mask:0xf
	v_mov_b32_dpp v72, v60 row_shr:1 row_mask:0xf bank_mask:0xf
	v_add_f32_e32 v74, 1.0, v74
	v_add_f32_e32 v75, 1.0, v75
	v_rcp_f32_e32 v74, v74
	v_rcp_f32_e32 v75, v75
	v_mov_b32_dpp v73, v61 row_shr:1 row_mask:0xf bank_mask:0xf
	v_pk_fma_f32 v[76:77], v[116:117], v[78:79], v[132:133]
	v_mov_b32_e32 v98, 0
	v_pk_fma_f32 v[72:73], v[124:125], v[72:73], v[76:77]
	v_pk_mul_f32 v[70:71], v[70:71], v[74:75]
	v_pk_fma_f32 v[72:73], v[60:61], v[128:129], v[72:73]
	s_and_b64 vcc, exec, s[14:15]
	v_pk_mul_f32 v[70:71], v[72:73], v[70:71]
	v_cvt_pk_bf16_f32 v69, v70, v71
	v_add_u32_e32 v70, 0xa0, v186
	v_mad_i64_i32 v[160:161], s[6:7], v70, s29, v[66:67]
	v_lshl_add_u64 v[70:71], v[160:161], 0, v[102:103]
	global_store_dwordx2 v[70:71], v[68:69], off
	v_mov_b32_e32 v68, 0
	v_mov_b32_dpp v70, v64 row_ror:2 row_mask:0xf bank_mask:0xf
	v_mov_b32_dpp v71, v65 row_ror:2 row_mask:0xf bank_mask:0xf
	v_mov_b32_dpp v68, v64 row_ror:1 row_mask:0xf bank_mask:0xf
	v_mov_b32_dpp v70, v86 row_shr:2 row_mask:0xf bank_mask:0xf
	v_mov_b32_dpp v69, v65 row_ror:1 row_mask:0xf bank_mask:0xf
	v_mov_b32_dpp v71, v87 row_shr:2 row_mask:0xf bank_mask:0xf
	v_mov_b32_dpp v68, v86 row_shr:1 row_mask:0xf bank_mask:0xf
	v_mov_b32_dpp v64, v58 row_ror:1 row_mask:0xf bank_mask:0xf
	v_mov_b32_dpp v72, v58 row_ror:2 row_mask:0xf bank_mask:0xf
	v_mov_b32_dpp v69, v87 row_shr:1 row_mask:0xf bank_mask:0xf
	v_mov_b32_dpp v65, v59 row_ror:1 row_mask:0xf bank_mask:0xf
	v_mov_b32_dpp v73, v59 row_ror:2 row_mask:0xf bank_mask:0xf
	v_pk_fma_f32 v[58:59], v[138:139], v[70:71], v[150:151]
	v_mov_b32_dpp v72, v82 row_shr:2 row_mask:0xf bank_mask:0xf
	v_pk_fma_f32 v[58:59], v[142:143], v[68:69], v[58:59]
	v_mov_b32_dpp v73, v83 row_shr:2 row_mask:0xf bank_mask:0xf
	v_pk_fma_f32 v[58:59], v[86:87], v[146:147], v[58:59]
	v_mov_b32_dpp v64, v82 row_shr:1 row_mask:0xf bank_mask:0xf
	v_mul_f32_e32 v68, 0xbfb8aa3b, v58
	v_mul_f32_e32 v69, 0xbfb8aa3b, v59
	v_exp_f32_e32 v68, v68
	v_exp_f32_e32 v69, v69
	v_mov_b32_dpp v65, v83 row_shr:1 row_mask:0xf bank_mask:0xf
	v_pk_fma_f32 v[70:71], v[114:115], v[72:73], v[130:131]
	v_add_f32_e32 v68, 1.0, v68
	v_add_f32_e32 v69, 1.0, v69
	v_rcp_f32_e32 v68, v68
	v_rcp_f32_e32 v69, v69
	v_pk_fma_f32 v[64:65], v[122:123], v[64:65], v[70:71]
	v_pk_fma_f32 v[64:65], v[82:83], v[126:127], v[64:65]
	v_pk_mul_f32 v[58:59], v[58:59], v[68:69]
	v_pk_mul_f32 v[58:59], v[64:65], v[58:59]
	v_mov_b32_dpp v68, v62 row_ror:2 row_mask:0xf bank_mask:0xf
	v_mov_b32_dpp v69, v63 row_ror:2 row_mask:0xf bank_mask:0xf
	v_mov_b32_dpp v64, v62 row_ror:1 row_mask:0xf bank_mask:0xf
	v_mov_b32_dpp v68, v88 row_shr:2 row_mask:0xf bank_mask:0xf
	v_mov_b32_dpp v65, v63 row_ror:1 row_mask:0xf bank_mask:0xf
	v_mov_b32_dpp v69, v89 row_shr:2 row_mask:0xf bank_mask:0xf
	v_mov_b32_dpp v64, v88 row_shr:1 row_mask:0xf bank_mask:0xf
	v_mov_b32_dpp v62, v60 row_ror:1 row_mask:0xf bank_mask:0xf
	v_mov_b32_dpp v70, v60 row_ror:2 row_mask:0xf bank_mask:0xf
	v_mov_b32_dpp v65, v89 row_shr:1 row_mask:0xf bank_mask:0xf
	v_mov_b32_dpp v63, v61 row_ror:1 row_mask:0xf bank_mask:0xf
	v_mov_b32_dpp v71, v61 row_ror:2 row_mask:0xf bank_mask:0xf
	v_pk_fma_f32 v[60:61], v[140:141], v[68:69], v[152:153]
	v_mov_b32_dpp v70, v84 row_shr:2 row_mask:0xf bank_mask:0xf
	v_pk_fma_f32 v[60:61], v[144:145], v[64:65], v[60:61]
	v_mov_b32_dpp v71, v85 row_shr:2 row_mask:0xf bank_mask:0xf
	v_pk_fma_f32 v[60:61], v[88:89], v[148:149], v[60:61]
	v_mov_b32_dpp v62, v84 row_shr:1 row_mask:0xf bank_mask:0xf
	v_mul_f32_e32 v64, 0xbfb8aa3b, v60
	v_mul_f32_e32 v65, 0xbfb8aa3b, v61
	v_exp_f32_e32 v64, v64
	v_exp_f32_e32 v65, v65
	v_mov_b32_dpp v63, v85 row_shr:1 row_mask:0xf bank_mask:0xf
	v_pk_fma_f32 v[68:69], v[116:117], v[70:71], v[132:133]
	v_add_f32_e32 v64, 1.0, v64
	v_add_f32_e32 v65, 1.0, v65
	v_rcp_f32_e32 v64, v64
	v_rcp_f32_e32 v65, v65
	v_pk_fma_f32 v[62:63], v[124:125], v[62:63], v[68:69]
	v_cvt_pk_bf16_f32 v58, v58, v59
	v_pk_fma_f32 v[62:63], v[84:85], v[128:129], v[62:63]
	v_pk_mul_f32 v[60:61], v[60:61], v[64:65]
	v_mov_b32_e32 v100, 0
	v_pk_mul_f32 v[60:61], v[62:63], v[60:61]
	v_mov_b32_e32 v101, 0
	v_cvt_pk_bf16_f32 v59, v60, v61
	v_add_u32_e32 v60, 0xb0, v186
	v_mad_i64_i32 v[114:115], s[6:7], v60, s29, v[66:67]
	v_lshl_add_u64 v[60:61], v[114:115], 0, v[102:103]
	global_store_dwordx2 v[60:61], v[58:59], off
	v_or_b32_e32 v58, 4, v188
	v_ashrrev_i32_e32 v59, 31, v58
	v_lshlrev_b64 v[60:61], 2, v[188:189]
	v_lshlrev_b64 v[70:71], 2, v[58:59]
	v_lshl_add_u64 v[62:63], s[68:69], 0, v[60:61]
	v_lshl_add_u64 v[58:59], s[38:39], 0, v[70:71]
	global_load_dwordx4 v[74:77], v[62:63], off offset:16
	global_load_dwordx4 v[78:81], v[58:59], off
	v_lshl_add_u64 v[58:59], s[42:43], 0, v[70:71]
	global_load_dwordx4 v[82:85], v[58:59], off
	v_lshl_add_u64 v[58:59], s[70:71], 0, v[60:61]
	global_load_dwordx4 v[86:89], v[58:59], off offset:16
	v_lshl_add_u64 v[58:59], s[44:45], 0, v[70:71]
	v_lshl_add_u64 v[62:63], s[56:57], 0, v[70:71]
	v_lshl_add_u64 v[66:67], s[20:21], 0, v[70:71]
	v_lshl_add_u64 v[70:71], s[8:9], 0, v[70:71]
	global_load_dwordx4 v[58:61], v[58:59], off
	s_nop 0
	global_load_dwordx4 v[62:65], v[62:63], off
	v_mov_b32_e32 v102, 0
	global_load_dwordx4 v[66:69], v[66:67], off
	v_mov_b32_e32 v103, 0
	global_load_dwordx4 v[70:73], v[70:71], off
	v_mov_b32_e32 v104, 0
	v_mov_b32_e32 v105, 0
	v_mov_b32_e32 v106, 0
	v_mov_b32_e32 v107, 0
	s_cbranch_vccnz .LBB0_789
	s_add_i32 s6, 0, 0x20000
	v_lshl_add_u32 v99, v187, 6, s6
	ds_read_b128 v[104:107], v99 offset:16
	ds_read_b128 v[100:103], v99 offset:48
.LBB0_789:
	v_mov_b32_e32 v197, v196
	v_mov_b32_e32 v116, v196
	v_mov_b32_e32 v117, v196
	v_pk_mul_f32 v[48:49], v[48:49], v[116:117]
	v_pk_mul_f32 v[122:123], v[46:47], v[196:197]
	v_pk_mul_f32 v[46:47], v[40:41], v[116:117]
	v_pk_mul_f32 v[116:117], v[38:39], v[196:197]
	v_mov_b32_e32 v38, v110
	v_mov_b32_e32 v39, v110
	v_pk_mul_f32 v[40:41], v[44:45], v[38:39]
	v_pk_mul_f32 v[36:37], v[36:37], v[38:39]
	s_waitcnt lgkmcnt(1)
	v_mov_b32_dpp v44, v104 row_ror:2 row_mask:0xf bank_mask:0xf
	v_mov_b32_dpp v45, v105 row_ror:2 row_mask:0xf bank_mask:0xf
	v_mov_b32_dpp v38, v104 row_ror:1 row_mask:0xf bank_mask:0xf
	v_mov_b32_dpp v44, v90 row_shr:2 row_mask:0xf bank_mask:0xf
	v_mov_b32_dpp v39, v105 row_ror:1 row_mask:0xf bank_mask:0xf
	v_mov_b32_dpp v45, v91 row_shr:2 row_mask:0xf bank_mask:0xf
	v_mov_b32_dpp v38, v90 row_shr:1 row_mask:0xf bank_mask:0xf
	v_mov_b32_dpp v39, v91 row_shr:1 row_mask:0xf bank_mask:0xf
	s_waitcnt vmcnt(4)
	v_pk_fma_f32 v[44:45], v[74:75], v[44:45], v[86:87]
	v_mov_b32_e32 v111, v110
	v_pk_fma_f32 v[38:39], v[78:79], v[38:39], v[44:45]
	v_pk_mul_f32 v[42:43], v[42:43], v[110:111]
	v_pk_fma_f32 v[38:39], v[90:91], v[82:83], v[38:39]
	v_pk_mul_f32 v[34:35], v[34:35], v[110:111]
	v_mul_f32_e32 v44, 0xbfb8aa3b, v38
	v_mul_f32_e32 v45, 0xbfb8aa3b, v39
	v_exp_f32_e32 v44, v44
	v_exp_f32_e32 v45, v45
	v_add_f32_e32 v44, 1.0, v44
	v_add_f32_e32 v45, 1.0, v45
	s_waitcnt lgkmcnt(0)
	v_mov_b32_dpp v110, v100 row_ror:2 row_mask:0xf bank_mask:0xf
	v_mov_b32_dpp v111, v101 row_ror:2 row_mask:0xf bank_mask:0xf
	v_rcp_f32_e32 v44, v44
	v_rcp_f32_e32 v45, v45
	v_mov_b32_dpp v104, v100 row_ror:1 row_mask:0xf bank_mask:0xf
	v_mov_b32_dpp v110, v94 row_shr:2 row_mask:0xf bank_mask:0xf
	v_mov_b32_dpp v105, v101 row_ror:1 row_mask:0xf bank_mask:0xf
	v_mov_b32_dpp v111, v95 row_shr:2 row_mask:0xf bank_mask:0xf
	v_mov_b32_dpp v104, v94 row_shr:1 row_mask:0xf bank_mask:0xf
	v_mov_b32_dpp v105, v95 row_shr:1 row_mask:0xf bank_mask:0xf
	s_waitcnt vmcnt(0)
	v_pk_fma_f32 v[100:101], v[58:59], v[110:111], v[70:71]
	v_pk_mul_f32 v[38:39], v[38:39], v[44:45]
	v_pk_fma_f32 v[100:101], v[62:63], v[104:105], v[100:101]
	v_pk_fma_f32 v[100:101], v[94:95], v[66:67], v[100:101]
	v_pk_mul_f32 v[38:39], v[100:101], v[38:39]
	v_mov_b32_dpp v44, v106 row_ror:1 row_mask:0xf bank_mask:0xf
	v_mov_b32_dpp v100, v106 row_ror:2 row_mask:0xf bank_mask:0xf
	v_mov_b32_dpp v101, v107 row_ror:2 row_mask:0xf bank_mask:0xf
	v_mov_b32_dpp v45, v107 row_ror:1 row_mask:0xf bank_mask:0xf
	v_mov_b32_dpp v100, v92 row_shr:2 row_mask:0xf bank_mask:0xf
	v_mov_b32_dpp v101, v93 row_shr:2 row_mask:0xf bank_mask:0xf
	v_mov_b32_dpp v44, v92 row_shr:1 row_mask:0xf bank_mask:0xf
	v_mov_b32_dpp v45, v93 row_shr:1 row_mask:0xf bank_mask:0xf
	v_pk_fma_f32 v[100:101], v[76:77], v[100:101], v[88:89]
	v_pk_fma_f32 v[44:45], v[80:81], v[44:45], v[100:101]
	v_pk_fma_f32 v[44:45], v[92:93], v[84:85], v[44:45]
	v_mul_f32_e32 v99, 0xbfb8aa3b, v44
	v_exp_f32_e32 v99, v99
	v_mul_f32_e32 v100, 0xbfb8aa3b, v45
	v_exp_f32_e32 v101, v100
	v_mov_b32_dpp v106, v102 row_ror:2 row_mask:0xf bank_mask:0xf
	v_add_f32_e32 v99, 1.0, v99
	v_rcp_f32_e32 v100, v99
	v_add_f32_e32 v99, 1.0, v101
	v_mov_b32_dpp v107, v103 row_ror:2 row_mask:0xf bank_mask:0xf
	v_rcp_f32_e32 v101, v99
	v_mov_b32_dpp v104, v102 row_ror:1 row_mask:0xf bank_mask:0xf
	v_mov_b32_dpp v106, v96 row_shr:2 row_mask:0xf bank_mask:0xf
	v_mov_b32_dpp v105, v103 row_ror:1 row_mask:0xf bank_mask:0xf
	v_mov_b32_dpp v107, v97 row_shr:2 row_mask:0xf bank_mask:0xf
	v_mov_b32_dpp v104, v96 row_shr:1 row_mask:0xf bank_mask:0xf
	v_mov_b32_dpp v105, v97 row_shr:1 row_mask:0xf bank_mask:0xf
	v_pk_fma_f32 v[102:103], v[60:61], v[106:107], v[72:73]
	v_pk_mul_f32 v[44:45], v[44:45], v[100:101]
	v_pk_fma_f32 v[102:103], v[64:65], v[104:105], v[102:103]
	v_cvt_pk_bf16_f32 v100, v38, v39
	v_pk_fma_f32 v[102:103], v[96:97], v[68:69], v[102:103]
	v_lshlrev_b64 v[38:39], 1, v[188:189]
	v_pk_mul_f32 v[44:45], v[102:103], v[44:45]
	v_cvt_pk_bf16_f32 v101, v44, v45
	v_lshl_add_u64 v[44:45], v[108:109], 0, v[38:39]
	global_store_dwordx2 v[44:45], v[100:101], off offset:8
	v_mov_b32_dpp v100, v90 row_ror:2 row_mask:0xf bank_mask:0xf
	v_mov_b32_dpp v101, v91 row_ror:2 row_mask:0xf bank_mask:0xf
	v_mov_b32_dpp v44, v90 row_ror:1 row_mask:0xf bank_mask:0xf
	v_mov_b32_dpp v100, v122 row_shr:2 row_mask:0xf bank_mask:0xf
	v_mov_b32_dpp v45, v91 row_ror:1 row_mask:0xf bank_mask:0xf
	v_mov_b32_dpp v101, v123 row_shr:2 row_mask:0xf bank_mask:0xf
	v_mov_b32_dpp v44, v122 row_shr:1 row_mask:0xf bank_mask:0xf
	v_mov_b32_dpp v90, v94 row_ror:1 row_mask:0xf bank_mask:0xf
	v_mov_b32_dpp v102, v94 row_ror:2 row_mask:0xf bank_mask:0xf
	v_mov_b32_dpp v45, v123 row_shr:1 row_mask:0xf bank_mask:0xf
	v_mov_b32_dpp v91, v95 row_ror:1 row_mask:0xf bank_mask:0xf
	v_mov_b32_dpp v103, v95 row_ror:2 row_mask:0xf bank_mask:0xf
	v_pk_fma_f32 v[94:95], v[74:75], v[100:101], v[86:87]
	v_mov_b32_dpp v102, v116 row_shr:2 row_mask:0xf bank_mask:0xf
	v_pk_fma_f32 v[44:45], v[78:79], v[44:45], v[94:95]
	v_mov_b32_dpp v103, v117 row_shr:2 row_mask:0xf bank_mask:0xf
	v_pk_fma_f32 v[44:45], v[122:123], v[82:83], v[44:45]
	v_mov_b32_dpp v90, v116 row_shr:1 row_mask:0xf bank_mask:0xf
	v_mul_f32_e32 v94, 0xbfb8aa3b, v44
	v_mul_f32_e32 v95, 0xbfb8aa3b, v45
	v_exp_f32_e32 v94, v94
	v_exp_f32_e32 v95, v95
	v_mov_b32_dpp v91, v117 row_shr:1 row_mask:0xf bank_mask:0xf
	v_pk_fma_f32 v[100:101], v[58:59], v[102:103], v[70:71]
	v_add_f32_e32 v94, 1.0, v94
	v_add_f32_e32 v95, 1.0, v95
	v_rcp_f32_e32 v94, v94
	v_rcp_f32_e32 v95, v95
	v_pk_fma_f32 v[90:91], v[62:63], v[90:91], v[100:101]
	v_pk_fma_f32 v[90:91], v[116:117], v[66:67], v[90:91]
	v_pk_mul_f32 v[44:45], v[44:45], v[94:95]
	v_pk_mul_f32 v[44:45], v[90:91], v[44:45]
	v_mov_b32_dpp v94, v92 row_ror:2 row_mask:0xf bank_mask:0xf
	v_mov_b32_dpp v95, v93 row_ror:2 row_mask:0xf bank_mask:0xf
	v_mov_b32_dpp v90, v92 row_ror:1 row_mask:0xf bank_mask:0xf
	v_mov_b32_dpp v94, v48 row_shr:2 row_mask:0xf bank_mask:0xf
	v_mov_b32_dpp v91, v93 row_ror:1 row_mask:0xf bank_mask:0xf
	v_mov_b32_dpp v95, v49 row_shr:2 row_mask:0xf bank_mask:0xf
	v_mov_b32_dpp v90, v48 row_shr:1 row_mask:0xf bank_mask:0xf
	v_mov_b32_dpp v91, v49 row_shr:1 row_mask:0xf bank_mask:0xf
	v_pk_fma_f32 v[94:95], v[76:77], v[94:95], v[88:89]
	v_pk_fma_f32 v[90:91], v[80:81], v[90:91], v[94:95]
	v_pk_fma_f32 v[90:91], v[48:49], v[84:85], v[90:91]
	v_mov_b32_dpp v100, v96 row_ror:2 row_mask:0xf bank_mask:0xf
	v_mul_f32_e32 v94, 0xbfb8aa3b, v90
	v_mul_f32_e32 v95, 0xbfb8aa3b, v91
	v_exp_f32_e32 v94, v94
	v_exp_f32_e32 v95, v95
	v_mov_b32_dpp v101, v97 row_ror:2 row_mask:0xf bank_mask:0xf
	v_add_f32_e32 v94, 1.0, v94
	v_add_f32_e32 v95, 1.0, v95
	v_rcp_f32_e32 v94, v94
	v_rcp_f32_e32 v95, v95
	v_mov_b32_dpp v92, v96 row_ror:1 row_mask:0xf bank_mask:0xf
	v_mov_b32_dpp v100, v46 row_shr:2 row_mask:0xf bank_mask:0xf
	v_mov_b32_dpp v93, v97 row_ror:1 row_mask:0xf bank_mask:0xf
	v_mov_b32_dpp v101, v47 row_shr:2 row_mask:0xf bank_mask:0xf
	v_mov_b32_dpp v92, v46 row_shr:1 row_mask:0xf bank_mask:0xf
	v_mov_b32_dpp v93, v47 row_shr:1 row_mask:0xf bank_mask:0xf
	v_pk_fma_f32 v[96:97], v[60:61], v[100:101], v[72:73]
	v_pk_mul_f32 v[90:91], v[90:91], v[94:95]
	v_pk_fma_f32 v[92:93], v[64:65], v[92:93], v[96:97]
	v_cvt_pk_bf16_f32 v44, v44, v45
	v_pk_fma_f32 v[92:93], v[46:47], v[68:69], v[92:93]
	v_pk_mul_f32 v[90:91], v[92:93], v[90:91]
	v_cvt_pk_bf16_f32 v45, v90, v91
	v_lshl_add_u64 v[90:91], v[112:113], 0, v[38:39]
	global_store_dwordx2 v[90:91], v[44:45], off offset:8
	v_mov_b32_e32 v44, 0
	v_mov_b32_dpp v90, v122 row_ror:2 row_mask:0xf bank_mask:0xf
	v_mov_b32_dpp v91, v123 row_ror:2 row_mask:0xf bank_mask:0xf
	v_mov_b32_dpp v44, v122 row_ror:1 row_mask:0xf bank_mask:0xf
	v_mov_b32_dpp v90, v42 row_shr:2 row_mask:0xf bank_mask:0xf
	v_mov_b32_dpp v45, v123 row_ror:1 row_mask:0xf bank_mask:0xf
	v_mov_b32_dpp v91, v43 row_shr:2 row_mask:0xf bank_mask:0xf
	v_mov_b32_dpp v44, v42 row_shr:1 row_mask:0xf bank_mask:0xf
	v_mov_b32_dpp v45, v43 row_shr:1 row_mask:0xf bank_mask:0xf
	v_pk_fma_f32 v[90:91], v[74:75], v[90:91], v[86:87]
	v_pk_fma_f32 v[44:45], v[78:79], v[44:45], v[90:91]
	v_mov_b32_dpp v94, v116 row_ror:2 row_mask:0xf bank_mask:0xf
	v_pk_fma_f32 v[44:45], v[42:43], v[82:83], v[44:45]
	v_mul_f32_e32 v90, 0xbfb8aa3b, v44
	v_mul_f32_e32 v91, 0xbfb8aa3b, v45
	v_exp_f32_e32 v90, v90
	v_exp_f32_e32 v91, v91
	v_mov_b32_dpp v95, v117 row_ror:2 row_mask:0xf bank_mask:0xf
	v_mov_b32_dpp v92, v116 row_ror:1 row_mask:0xf bank_mask:0xf
	v_add_f32_e32 v90, 1.0, v90
	v_add_f32_e32 v91, 1.0, v91
	v_rcp_f32_e32 v90, v90
	v_rcp_f32_e32 v91, v91
	v_mov_b32_dpp v94, v34 row_shr:2 row_mask:0xf bank_mask:0xf
	v_mov_b32_dpp v93, v117 row_ror:1 row_mask:0xf bank_mask:0xf
	v_mov_b32_dpp v95, v35 row_shr:2 row_mask:0xf bank_mask:0xf
	v_mov_b32_dpp v92, v34 row_shr:1 row_mask:0xf bank_mask:0xf
	v_mov_b32_dpp v93, v35 row_shr:1 row_mask:0xf bank_mask:0xf
	v_pk_fma_f32 v[94:95], v[58:59], v[94:95], v[70:71]
	v_pk_mul_f32 v[44:45], v[44:45], v[90:91]
	v_pk_fma_f32 v[92:93], v[62:63], v[92:93], v[94:95]
	v_pk_fma_f32 v[92:93], v[34:35], v[66:67], v[92:93]
	v_pk_mul_f32 v[44:45], v[92:93], v[44:45]
	v_mov_b32_dpp v90, v48 row_ror:1 row_mask:0xf bank_mask:0xf
	v_mov_b32_dpp v92, v48 row_ror:2 row_mask:0xf bank_mask:0xf
	v_mov_b32_dpp v93, v49 row_ror:2 row_mask:0xf bank_mask:0xf
	v_mov_b32_e32 v48, 0
	v_mov_b32_dpp v92, v40 row_shr:2 row_mask:0xf bank_mask:0xf
	v_mov_b32_dpp v91, v49 row_ror:1 row_mask:0xf bank_mask:0xf
	v_mov_b32_dpp v93, v41 row_shr:2 row_mask:0xf bank_mask:0xf
	v_mov_b32_dpp v90, v40 row_shr:1 row_mask:0xf bank_mask:0xf
	v_mov_b32_dpp v48, v46 row_ror:1 row_mask:0xf bank_mask:0xf
	v_mov_b32_dpp v94, v46 row_ror:2 row_mask:0xf bank_mask:0xf
	v_mov_b32_dpp v91, v41 row_shr:1 row_mask:0xf bank_mask:0xf
	v_mov_b32_dpp v49, v47 row_ror:1 row_mask:0xf bank_mask:0xf
	v_mov_b32_dpp v95, v47 row_ror:2 row_mask:0xf bank_mask:0xf
	v_pk_fma_f32 v[46:47], v[76:77], v[92:93], v[88:89]
	v_mov_b32_dpp v94, v36 row_shr:2 row_mask:0xf bank_mask:0xf
	v_pk_fma_f32 v[46:47], v[80:81], v[90:91], v[46:47]
	v_mov_b32_dpp v95, v37 row_shr:2 row_mask:0xf bank_mask:0xf
	v_pk_fma_f32 v[46:47], v[40:41], v[84:85], v[46:47]
	v_mov_b32_dpp v48, v36 row_shr:1 row_mask:0xf bank_mask:0xf
	v_mul_f32_e32 v90, 0xbfb8aa3b, v46
	v_mul_f32_e32 v91, 0xbfb8aa3b, v47
	v_exp_f32_e32 v90, v90
	v_exp_f32_e32 v91, v91
	v_mov_b32_dpp v49, v37 row_shr:1 row_mask:0xf bank_mask:0xf
	v_pk_fma_f32 v[92:93], v[60:61], v[94:95], v[72:73]
	v_add_f32_e32 v90, 1.0, v90
	v_add_f32_e32 v91, 1.0, v91
	v_rcp_f32_e32 v90, v90
	v_rcp_f32_e32 v91, v91
	v_pk_fma_f32 v[48:49], v[64:65], v[48:49], v[92:93]
	v_cvt_pk_bf16_f32 v44, v44, v45
	v_pk_fma_f32 v[48:49], v[36:37], v[68:69], v[48:49]
	v_pk_mul_f32 v[46:47], v[46:47], v[90:91]
	s_and_b64 vcc, exec, s[16:17]
	v_pk_mul_f32 v[46:47], v[48:49], v[46:47]
	v_cvt_pk_bf16_f32 v45, v46, v47
	v_lshl_add_u64 v[46:47], v[158:159], 0, v[38:39]
	global_store_dwordx2 v[46:47], v[44:45], off offset:8
	v_mov_b32_e32 v44, 0
	v_mov_b32_dpp v46, v42 row_ror:2 row_mask:0xf bank_mask:0xf
	v_mov_b32_dpp v47, v43 row_ror:2 row_mask:0xf bank_mask:0xf
	v_mov_b32_dpp v44, v42 row_ror:1 row_mask:0xf bank_mask:0xf
	v_mov_b32_dpp v46, v54 row_shr:2 row_mask:0xf bank_mask:0xf
	v_mov_b32_dpp v45, v43 row_ror:1 row_mask:0xf bank_mask:0xf
	v_mov_b32_dpp v47, v55 row_shr:2 row_mask:0xf bank_mask:0xf
	v_mov_b32_dpp v44, v54 row_shr:1 row_mask:0xf bank_mask:0xf
	v_mov_b32_dpp v42, v34 row_ror:1 row_mask:0xf bank_mask:0xf
	v_mov_b32_dpp v48, v34 row_ror:2 row_mask:0xf bank_mask:0xf
	v_mov_b32_dpp v45, v55 row_shr:1 row_mask:0xf bank_mask:0xf
	v_mov_b32_dpp v43, v35 row_ror:1 row_mask:0xf bank_mask:0xf
	v_mov_b32_dpp v49, v35 row_ror:2 row_mask:0xf bank_mask:0xf
	v_pk_fma_f32 v[34:35], v[74:75], v[46:47], v[86:87]
	v_mov_b32_dpp v48, v50 row_shr:2 row_mask:0xf bank_mask:0xf
	v_pk_fma_f32 v[34:35], v[78:79], v[44:45], v[34:35]
	v_mov_b32_dpp v49, v51 row_shr:2 row_mask:0xf bank_mask:0xf
	v_pk_fma_f32 v[34:35], v[54:55], v[82:83], v[34:35]
	v_mov_b32_dpp v42, v50 row_shr:1 row_mask:0xf bank_mask:0xf
	v_mul_f32_e32 v44, 0xbfb8aa3b, v34
	v_mul_f32_e32 v45, 0xbfb8aa3b, v35
	v_exp_f32_e32 v44, v44
	v_exp_f32_e32 v45, v45
	v_mov_b32_dpp v43, v51 row_shr:1 row_mask:0xf bank_mask:0xf
	v_pk_fma_f32 v[46:47], v[58:59], v[48:49], v[70:71]
	v_add_f32_e32 v44, 1.0, v44
	v_add_f32_e32 v45, 1.0, v45
	v_rcp_f32_e32 v44, v44
	v_rcp_f32_e32 v45, v45
	v_pk_fma_f32 v[42:43], v[62:63], v[42:43], v[46:47]
	v_pk_fma_f32 v[42:43], v[50:51], v[66:67], v[42:43]
	v_pk_mul_f32 v[34:35], v[34:35], v[44:45]
	v_pk_mul_f32 v[34:35], v[42:43], v[34:35]
	v_mov_b32_dpp v44, v40 row_ror:2 row_mask:0xf bank_mask:0xf
	v_mov_b32_dpp v45, v41 row_ror:2 row_mask:0xf bank_mask:0xf
	v_mov_b32_dpp v42, v40 row_ror:1 row_mask:0xf bank_mask:0xf
	v_mov_b32_dpp v44, v56 row_shr:2 row_mask:0xf bank_mask:0xf
	v_mov_b32_dpp v43, v41 row_ror:1 row_mask:0xf bank_mask:0xf
	v_mov_b32_dpp v45, v57 row_shr:2 row_mask:0xf bank_mask:0xf
	v_mov_b32_dpp v42, v56 row_shr:1 row_mask:0xf bank_mask:0xf
	v_mov_b32_dpp v40, v36 row_ror:1 row_mask:0xf bank_mask:0xf
	v_mov_b32_dpp v46, v36 row_ror:2 row_mask:0xf bank_mask:0xf
	v_mov_b32_dpp v43, v57 row_shr:1 row_mask:0xf bank_mask:0xf
	v_mov_b32_dpp v41, v37 row_ror:1 row_mask:0xf bank_mask:0xf
	v_mov_b32_dpp v47, v37 row_ror:2 row_mask:0xf bank_mask:0xf
	v_pk_fma_f32 v[36:37], v[76:77], v[44:45], v[88:89]
	v_mov_b32_dpp v46, v52 row_shr:2 row_mask:0xf bank_mask:0xf
	v_pk_fma_f32 v[36:37], v[80:81], v[42:43], v[36:37]
	v_mov_b32_dpp v47, v53 row_shr:2 row_mask:0xf bank_mask:0xf
	v_pk_fma_f32 v[36:37], v[56:57], v[84:85], v[36:37]
	v_mov_b32_dpp v40, v52 row_shr:1 row_mask:0xf bank_mask:0xf
	v_mul_f32_e32 v42, 0xbfb8aa3b, v36
	v_mul_f32_e32 v43, 0xbfb8aa3b, v37
	v_exp_f32_e32 v42, v42
	v_exp_f32_e32 v43, v43
	v_mov_b32_dpp v41, v53 row_shr:1 row_mask:0xf bank_mask:0xf
	v_pk_fma_f32 v[44:45], v[60:61], v[46:47], v[72:73]
	v_add_f32_e32 v42, 1.0, v42
	v_add_f32_e32 v43, 1.0, v43
	v_rcp_f32_e32 v42, v42
	v_rcp_f32_e32 v43, v43
	v_pk_fma_f32 v[40:41], v[64:65], v[40:41], v[44:45]
	v_cvt_pk_bf16_f32 v34, v34, v35
	v_pk_fma_f32 v[40:41], v[52:53], v[68:69], v[40:41]
	v_pk_mul_f32 v[36:37], v[36:37], v[42:43]
	v_mov_b32_e32 v99, 0
	v_pk_mul_f32 v[36:37], v[40:41], v[36:37]
	v_mov_b32_e32 v100, 0
	v_cvt_pk_bf16_f32 v35, v36, v37
	v_lshl_add_u64 v[36:37], v[118:119], 0, v[38:39]
	global_store_dwordx2 v[36:37], v[34:35], off offset:8
	v_mov_b32_e32 v101, 0
	v_mov_b32_e32 v34, 0
	v_mov_b32_e32 v35, 0
	v_mov_b32_e32 v36, 0
	v_mov_b32_e32 v37, 0
	s_cbranch_vccnz .LBB0_791
	s_add_i32 s6, 0, 0x20000
	v_lshl_add_u32 v40, v121, 6, s6
	ds_read_b128 v[34:37], v40 offset:16
	ds_read_b128 v[98:101], v40 offset:48
